# attention QK (map 0) LDS reads software-pipelined with counted lgkmcnt
# baseline (speedup 1.0000x reference)
; #define LAS __attribute__((address_space(3)))
; #define MFMA16(a, b, c) __builtin_amdgcn_mfma_f32_16x16x32_bf16(a, b, c, 0, 0, 0)
; __device__ __forceinline__ void attn_unit(const Args& c, int l, int b, int h, int qb, float lam, float lam_init, LAS unsigned char* lds) {
;     ...
;             for (int kb = 0; kb < 8; ++kb) {
;                 s[kb] = (f32x4){0.f, 0.f, 0.f, 0.f};
; #pragma unroll
;                 for (int ks = 0; ks < 2; ++ks) { const bf16x8 a = *(const LAS bf16x8*)(Kt + (16 * kb + r) * 136 + m * 64 + ks * 32 + q4 * 8); s[kb] = MFMA16(a, qf[m][ks], s[kb]); }
;             }
;             if (kt == qb) {
;                 const int qpos = 128 * qb + 16 * w + r;
; #pragma unroll
;                 for (int kb = 0; kb < 8; ++kb)
; #pragma unroll
;                     for (int e = 0; e < 4; ++e) if (128 * kt + 16 * kb + 4 * q4 + e > qpos) s[kb][e] = -INFINITY;
;             }
.LBB0_247:
	s_waitcnt lgkmcnt(0)
	s_barrier
	ds_read_b128 v[114:117], v212
	ds_read_b128 v[150:153], v212 offset:64
	ds_read_b128 v[118:121], v212 offset:4352
	ds_read_b128 v[154:157], v212 offset:4416
	ds_read_b128 v[122:125], v212 offset:8704
	ds_read_b128 v[158:161], v212 offset:8768
	ds_read_b128 v[126:129], v212 offset:13056
	ds_read_b128 v[162:165], v212 offset:13120
	v_add_u32_e32 v214, s5, v208
	s_cmp_eq_u32 s22, s35
	s_cselect_b64 s[16:17], -1, 0
	s_cmp_lg_u32 s22, s35
	s_waitcnt lgkmcnt(6)
	v_mfma_f32_16x16x32_bf16 v[114:117], v[114:117], v[54:57], 0
	v_mfma_f32_16x16x32_bf16 v[114:117], v[150:153], v[50:53], v[114:117]
	ds_read_b128 v[130:133], v212 offset:17408
	ds_read_b128 v[166:169], v212 offset:17472
	s_waitcnt lgkmcnt(6)
	v_mfma_f32_16x16x32_bf16 v[118:121], v[118:121], v[54:57], 0
	v_mfma_f32_16x16x32_bf16 v[118:121], v[154:157], v[50:53], v[118:121]
	ds_read_b128 v[134:137], v212 offset:21760
	ds_read_b128 v[170:173], v212 offset:21824
	s_waitcnt lgkmcnt(6)
	v_mfma_f32_16x16x32_bf16 v[122:125], v[122:125], v[54:57], 0
	v_mfma_f32_16x16x32_bf16 v[122:125], v[158:161], v[50:53], v[122:125]
	ds_read_b128 v[138:141], v212 offset:26112
	ds_read_b128 v[174:177], v212 offset:26176
	s_waitcnt lgkmcnt(6)
	v_mfma_f32_16x16x32_bf16 v[126:129], v[126:129], v[54:57], 0
	v_mfma_f32_16x16x32_bf16 v[126:129], v[162:165], v[50:53], v[126:129]
	ds_read_b128 v[142:145], v212 offset:30464
	ds_read_b128 v[180:183], v212 offset:30528
	s_waitcnt lgkmcnt(6)
	v_mfma_f32_16x16x32_bf16 v[130:133], v[130:133], v[54:57], 0
	v_mfma_f32_16x16x32_bf16 v[130:133], v[166:169], v[50:53], v[130:133]
	s_waitcnt lgkmcnt(4)
	v_mfma_f32_16x16x32_bf16 v[134:137], v[134:137], v[54:57], 0
	v_mfma_f32_16x16x32_bf16 v[134:137], v[170:173], v[50:53], v[134:137]
	s_waitcnt lgkmcnt(2)
	v_mfma_f32_16x16x32_bf16 v[138:141], v[138:141], v[54:57], 0
	v_mfma_f32_16x16x32_bf16 v[138:141], v[174:177], v[50:53], v[138:141]
	s_waitcnt lgkmcnt(0)
	v_mfma_f32_16x16x32_bf16 v[142:145], v[142:145], v[54:57], 0
	v_mfma_f32_16x16x32_bf16 v[142:145], v[180:183], v[50:53], v[142:145]
	s_cbranch_scc1 .LBB0_249
	v_add_u32_e32 v245, 2, v214
	v_add_u32_e32 v246, 3, v214
	v_add_u32_e32 v242, 16, v214
	v_add_u32_e32 v241, 17, v214
	v_add_u32_e32 v244, 18, v214
	v_add_u32_e32 v243, 19, v214
	v_add_u32_e32 v237, 32, v214
	v_add_u32_e32 v240, 33, v214
	v_add_u32_e32 v239, 34, v214
	v_add_u32_e32 v238, 35, v214
	v_add_u32_e32 v235, 48, v214
	v_add_u32_e32 v234, 49, v214
	v_add_u32_e32 v233, 50, v214
	v_add_u32_e32 v236, 51, v214
	v_add_u32_e32 v230, 64, v214
	v_add_u32_e32 v229, 0x41, v214
	v_add_u32_e32 v232, 0x42, v214
	v_add_u32_e32 v231, 0x43, v214
	v_add_u32_e32 v225, 0x50, v214
	v_add_u32_e32 v228, 0x51, v214
	v_add_u32_e32 v227, 0x52, v214
	v_add_u32_e32 v226, 0x53, v214
	v_add_u32_e32 v224, 0x60, v214
	v_add_u32_e32 v223, 0x61, v214
	v_add_u32_e32 v222, 0x62, v214
	v_add_u32_e32 v221, 0x63, v214
	v_add_u32_e32 v220, 0x70, v214
	v_add_u32_e32 v219, 0x71, v214
	v_add_u32_e32 v218, 0x72, v214
	v_add_u32_e32 v217, 0x73, v214
	v_cmp_gt_i32_e64 s[44:45], v214, v209
	v_cmp_lt_i32_e64 s[6:7], v214, v209
	v_cmp_le_i32_e32 vcc, v245, v209
	v_cmp_le_i32_e64 s[12:13], v246, v209
	v_cmp_gt_i32_e64 s[94:95], v242, v209
	v_cmp_le_i32_e64 s[96:97], v241, v209
	v_cmp_le_i32_e64 s[10:11], v244, v209
	v_cmp_le_i32_e64 s[8:9], v243, v209
	v_cmp_gt_i32_e64 s[86:87], v237, v209
	v_cmp_le_i32_e64 s[88:89], v240, v209
	v_cmp_le_i32_e64 s[90:91], v239, v209
	v_cmp_le_i32_e64 s[92:93], v238, v209
	v_cmp_gt_i32_e64 s[78:79], v235, v209
	v_cmp_le_i32_e64 s[80:81], v234, v209
	v_cmp_le_i32_e64 s[82:83], v233, v209
	v_cmp_le_i32_e64 s[84:85], v236, v209
	v_cmp_gt_i32_e64 s[70:71], v230, v209
	v_cmp_le_i32_e64 s[72:73], v229, v209
	v_cmp_le_i32_e64 s[74:75], v232, v209
	v_cmp_le_i32_e64 s[76:77], v231, v209
	v_cmp_gt_i32_e64 s[62:63], v225, v209
	v_cmp_le_i32_e64 s[64:65], v228, v209
	v_cmp_le_i32_e64 s[66:67], v227, v209
	v_cmp_le_i32_e64 s[68:69], v226, v209
	v_cmp_gt_i32_e64 s[54:55], v224, v209
	v_cmp_le_i32_e64 s[56:57], v223, v209
	v_cmp_le_i32_e64 s[58:59], v222, v209
	v_cmp_le_i32_e64 s[60:61], v221, v209
	v_cmp_gt_i32_e64 s[46:47], v220, v209
	v_cmp_le_i32_e64 s[48:49], v219, v209
	v_cmp_le_i32_e64 s[50:51], v218, v209
	v_cmp_le_i32_e64 s[52:53], v217, v209
	v_mov_b32_e32 v146, s23
	v_cndmask_b32_e64 v146, v114, v146, s[44:45]
	v_cndmask_b32_e64 v114, v146, v114, s[6:7]
	v_mov_b32_e32 v146, s23
	v_cndmask_b32_e64 v115, v197, v115, s[6:7]
	v_cndmask_b32_e32 v116, v197, v116, vcc
	v_cndmask_b32_e64 v117, v197, v117, s[12:13]
	v_cndmask_b32_e64 v118, v118, v146, s[94:95]
	v_cndmask_b32_e64 v119, v197, v119, s[96:97]
	v_cndmask_b32_e64 v120, v197, v120, s[10:11]
	v_cndmask_b32_e64 v121, v197, v121, s[8:9]
	v_cndmask_b32_e64 v122, v122, v146, s[86:87]
	v_cndmask_b32_e64 v123, v197, v123, s[88:89]
	v_cndmask_b32_e64 v124, v197, v124, s[90:91]
	v_cndmask_b32_e64 v125, v197, v125, s[92:93]
	v_cndmask_b32_e64 v126, v126, v146, s[78:79]
	v_cndmask_b32_e64 v127, v197, v127, s[80:81]
	v_cndmask_b32_e64 v128, v197, v128, s[82:83]
	v_cndmask_b32_e64 v129, v197, v129, s[84:85]
	v_cndmask_b32_e64 v130, v130, v146, s[70:71]
	v_cndmask_b32_e64 v131, v197, v131, s[72:73]
	v_cndmask_b32_e64 v132, v197, v132, s[74:75]
	v_cndmask_b32_e64 v133, v197, v133, s[76:77]
	v_cndmask_b32_e64 v134, v134, v146, s[62:63]
	v_cndmask_b32_e64 v135, v197, v135, s[64:65]
	v_cndmask_b32_e64 v136, v197, v136, s[66:67]
	v_cndmask_b32_e64 v137, v197, v137, s[68:69]
	v_cndmask_b32_e64 v138, v138, v146, s[54:55]
	v_cndmask_b32_e64 v139, v197, v139, s[56:57]
	v_cndmask_b32_e64 v140, v197, v140, s[58:59]
	v_cndmask_b32_e64 v141, v197, v141, s[60:61]
	v_cndmask_b32_e64 v142, v142, v146, s[46:47]
	v_cndmask_b32_e64 v143, v197, v143, s[48:49]
	v_cndmask_b32_e64 v144, v197, v144, s[50:51]
	v_cndmask_b32_e64 v145, v197, v145, s[52:53]
